# grid seams: flat per-XCC arrival counters bumped by every XCC leader, no TOP round trip, two polls in flight
# speedup vs baseline: 1.0304x; 1.0018x over previous
.LBB0_176:
	s_or_b64 exec, exec, s[14:15]
	v_cvt_f32_u32_e32 v4, v2
	s_waitcnt vmcnt(0)
	v_readfirstlane_b32 s12, v3
	v_sub_u32_e32 v3, 0, v2
	v_rcp_iflag_f32_e32 v4, v4
	v_add_u32_e32 v5, s12, v1
	v_mul_f32_e32 v4, 0x4f7ffffe, v4
	v_cvt_u32_f32_e32 v4, v4
	v_mul_lo_u32 v1, v3, v4
	v_mul_hi_u32 v1, v4, v1
	v_add_u32_e32 v1, v4, v1
	v_mul_hi_u32 v1, v5, v1
	v_mul_lo_u32 v3, v1, v2
	v_sub_u32_e32 v3, v5, v3
	v_add_u32_e32 v4, 1, v1
	v_cmp_ge_u32_e32 vcc, v3, v2
	s_nop 1
	v_cndmask_b32_e32 v1, v1, v4, vcc
	v_sub_u32_e32 v4, v3, v2
	v_cndmask_b32_e32 v3, v3, v4, vcc
	v_add_u32_e32 v4, 1, v1
	v_cmp_ge_u32_e32 vcc, v3, v2
	v_add_u32_e32 v3, 1, v5
	s_nop 0
	v_cndmask_b32_e32 v1, v1, v4, vcc
	v_mul_lo_u32 v4, v2, v1
	v_add_u32_e32 v2, v4, v2
	v_cmp_ne_u32_e32 vcc, v3, v2
	s_waitcnt lgkmcnt(0)
	v_mad_u32_u24 v1, v1, v0, v0
	v_mov_b32_e32 v3, 0
	s_add_u32 s18, s6, 0x2400
	s_addc_u32 s19, s7, 0
	s_mov_b32 s34, 0
	s_cbranch_vccnz .Lxb_poll_0
	buffer_wbl2 sc1
	v_mov_b32_e32 v0, 0x3400
	v_mov_b32_e32 v2, 1
	s_waitcnt vmcnt(0)
	global_atomic_add v0, v2, s[10:11] offset:0
	global_atomic_add v0, v2, s[10:11] offset:256
	global_atomic_add v0, v2, s[10:11] offset:512
	global_atomic_add v0, v2, s[10:11] offset:768
	global_atomic_add v0, v2, s[10:11] offset:1024
	global_atomic_add v0, v2, s[10:11] offset:1280
	global_atomic_add v0, v2, s[10:11] offset:1536
	global_atomic_add v0, v2, s[10:11] offset:1792
	global_atomic_add v0, v2, s[10:11] offset:2048
	global_atomic_add v0, v2, s[10:11] offset:2304
	global_atomic_add v0, v2, s[10:11] offset:2560
	global_atomic_add v0, v2, s[10:11] offset:2816
	global_atomic_add v0, v2, s[10:11] offset:3072
	global_atomic_add v0, v2, s[10:11] offset:3328
	global_atomic_add v0, v2, s[10:11] offset:3584
	global_atomic_add v0, v2, s[10:11] offset:3840
.Lxb_poll_0:
	buffer_inv sc1
	global_load_dword v0, v3, s[18:19] sc1
	s_sleep 4
.Lxb_loop_0:
	global_load_dword v2, v3, s[18:19] sc1
	s_waitcnt vmcnt(1)
	v_cmp_ge_u32_e32 vcc, v0, v1
	s_cbranch_vccnz .Lxb_done_0
	global_load_dword v0, v3, s[18:19] sc1
	s_waitcnt vmcnt(1)
	v_cmp_ge_u32_e32 vcc, v2, v1
	s_cbranch_vccnz .Lxb_done_0
	s_add_i32 s34, s34, 1
	s_cmp_lt_u32 s34, 0x80000
	s_cbranch_scc1 .Lxb_loop_0
.Lxb_done_0:
	s_waitcnt vmcnt(0)
.LBB0_210:
	s_or_b64 exec, exec, s[4:5]
	s_mul_i32 s4, s25, s24
	s_ashr_i32 s25, s24, 31
	s_mul_i32 s33, s4, s33
	s_and_b32 s4, s24, 7
	s_cmp_eq_u32 s4, 0
	s_cselect_b64 s[4:5], -1, 0
	s_mov_b32 s27, 0
	v_writelane_b32 v255, s4, 0
	s_mov_b32 s94, 0x1fffe0
	v_mov_b32_e32 v169, 0
	v_writelane_b32 v255, s5, 1
	s_ashr_i32 s4, s24, 3
	s_cmpk_eq_i32 s24, 0x100
	v_writelane_b32 v255, s4, 2
	s_cselect_b64 s[92:93], -1, 0
	s_lshl_b32 s74, s24, 9
	s_lshl_b32 s75, s24, 6
	s_lshl_b32 s76, s24, 4
	s_lshl_b64 s[34:35], s[24:25], 15
	s_mov_b32 s80, 0x16000
	s_mov_b32 s81, 0x18000
	s_mov_b64 s[36:37], 0x80
	v_mov_b32_e32 v226, 0x358637bd
	s_mov_b32 s96, 0x90000
	s_add_i32 s95, 0, 0x20000
	s_add_i32 s87, 0, 0x20004
	v_mov_b32_e32 v233, 0x1000
	v_mov_b32_e32 v227, 1
	s_movk_i32 s97, 0x71
	s_movk_i32 s85, 0x1c00
	s_movk_i32 s86, 0x1000
	s_movk_i32 s88, 0x1600
	s_mov_b32 s77, 0xa8000
	v_mov_b64_e32 v[252:253], 0x100
	v_mbcnt_hi_u32_b32 v254, -1, v38
	v_mov_b32_e32 v232, 0xff800000
	s_mov_b32 s38, 0
	s_mov_b32 s40, 0x3db504f3
	s_waitcnt lgkmcnt(0)
	s_barrier
	s_branch .LBB0_214

.LBB0_283:
	s_or_b64 exec, exec, s[14:15]
	v_cvt_f32_u32_e32 v4, v2
	s_waitcnt vmcnt(0)
	v_readfirstlane_b32 s12, v3
	v_sub_u32_e32 v3, 0, v2
	v_rcp_iflag_f32_e32 v4, v4
	v_add_u32_e32 v5, s12, v1
	v_mul_f32_e32 v4, 0x4f7ffffe, v4
	v_cvt_u32_f32_e32 v4, v4
	v_mul_lo_u32 v1, v3, v4
	v_mul_hi_u32 v1, v4, v1
	v_add_u32_e32 v1, v4, v1
	v_mul_hi_u32 v1, v5, v1
	v_mul_lo_u32 v3, v1, v2
	v_sub_u32_e32 v3, v5, v3
	v_add_u32_e32 v4, 1, v1
	v_cmp_ge_u32_e32 vcc, v3, v2
	s_nop 1
	v_cndmask_b32_e32 v1, v1, v4, vcc
	v_sub_u32_e32 v4, v3, v2
	v_cndmask_b32_e32 v3, v3, v4, vcc
	v_add_u32_e32 v4, 1, v1
	v_cmp_ge_u32_e32 vcc, v3, v2
	v_add_u32_e32 v3, 1, v5
	s_nop 0
	v_cndmask_b32_e32 v1, v1, v4, vcc
	v_mul_lo_u32 v4, v2, v1
	v_add_u32_e32 v2, v4, v2
	v_cmp_ne_u32_e32 vcc, v3, v2
	s_waitcnt lgkmcnt(0)
	v_mad_u32_u24 v1, v1, v0, v0
	v_mov_b32_e32 v3, 0
	s_add_u32 s18, s10, 0x2400
	s_addc_u32 s19, s11, 0
	s_mov_b32 s26, 0
	s_cbranch_vccnz .Lxb_poll_1
	buffer_wbl2 sc1
	v_mov_b32_e32 v0, 0x3400
	v_mov_b32_e32 v2, 1
	s_waitcnt vmcnt(0)
	global_atomic_add v0, v2, s[6:7] offset:0
	global_atomic_add v0, v2, s[6:7] offset:256
	global_atomic_add v0, v2, s[6:7] offset:512
	global_atomic_add v0, v2, s[6:7] offset:768
	global_atomic_add v0, v2, s[6:7] offset:1024
	global_atomic_add v0, v2, s[6:7] offset:1280
	global_atomic_add v0, v2, s[6:7] offset:1536
	global_atomic_add v0, v2, s[6:7] offset:1792
	global_atomic_add v0, v2, s[6:7] offset:2048
	global_atomic_add v0, v2, s[6:7] offset:2304
	global_atomic_add v0, v2, s[6:7] offset:2560
	global_atomic_add v0, v2, s[6:7] offset:2816
	global_atomic_add v0, v2, s[6:7] offset:3072
	global_atomic_add v0, v2, s[6:7] offset:3328
	global_atomic_add v0, v2, s[6:7] offset:3584
	global_atomic_add v0, v2, s[6:7] offset:3840

.Lxb_loop_1:
	global_load_dword v2, v3, s[18:19] sc1
	s_waitcnt vmcnt(1)
	v_cmp_ge_u32_e32 vcc, v0, v1
	s_cbranch_vccnz .Lxb_done_1
	global_load_dword v0, v3, s[18:19] sc1
	s_waitcnt vmcnt(1)
	v_cmp_ge_u32_e32 vcc, v2, v1
	s_cbranch_vccnz .Lxb_done_1
	s_add_i32 s26, s26, 1
	s_cmp_lt_u32 s26, 0x80000
	s_cbranch_scc1 .Lxb_loop_1
.Lxb_done_1:
	s_waitcnt vmcnt(0)
.LBB0_317:
	s_or_b64 exec, exec, s[4:5]
	s_mov_b64 s[10:11], s[0:1]
	s_waitcnt lgkmcnt(0)
	s_barrier
	s_load_dwordx4 s[4:7], s[10:11], 0x58
	s_nop 0
	s_load_dwordx2 s[10:11], s[10:11], 0x90
	v_mbcnt_lo_u32_b32 v0, -1, 0
	v_mbcnt_hi_u32_b32 v0, -1, v0
	v_readlane_b32 s14, v255, 0
	v_add_u32_e32 v0, s3, v0
	v_readlane_b32 s15, v255, 1
	v_mov_b32_e32 v247, 0x1000
	s_mov_b32 s22, s2
	v_readfirstlane_b32 s12, v0
	s_andn2_b64 vcc, exec, s[14:15]
	s_cbranch_vccz .LBB0_319
	s_cmpk_gt_i32 s22, 0x1ff
	s_cbranch_scc0 .LBB0_320
	s_branch .LBB0_337

.Lxb_done_2:
	s_waitcnt vmcnt(0)
.LBB0_449:
	s_or_b64 exec, exec, s[4:5]
	s_mov_b64 s[12:13], s[0:1]
	s_waitcnt lgkmcnt(0)
	s_barrier
	s_load_dwordx2 s[10:11], s[12:13], 0x90
	v_mbcnt_lo_u32_b32 v0, -1, 0
	v_mbcnt_hi_u32_b32 v0, -1, v0
	s_mov_b32 s4, s2
	v_add_u32_e32 v53, s3, v0
	s_waitcnt lgkmcnt(0)
	s_add_u32 s6, s10, 0x8700000
	s_addc_u32 s7, s11, 0
	v_readfirstlane_b32 s5, v53
	s_cmpk_gt_i32 s4, 0xff
	v_lshlrev_b32_e32 v72, 3, v53
	s_cbranch_scc1 .LBB0_462
	s_load_dwordx2 s[12:13], s[12:13], 0x38
	s_mul_hi_u32 s15, s41, 0x1800
	s_mulk_i32 s41, 0x1800
	v_and_b32_e32 v52, 0x1f8, v72
	v_lshlrev_b32_e32 v168, 2, v52
	s_waitcnt lgkmcnt(0)
	s_add_u32 s14, s12, s41
	s_addc_u32 s15, s13, s15
	s_add_u32 s12, s10, 0xf700000
	v_ashrrev_i32_e32 v0, 6, v53
	s_addc_u32 s13, s11, 0
	v_lshl_add_u64 v[54:55], s[14:15], 0, v[168:169]
	s_mov_b64 s[14:15], 0x1000
	v_lshlrev_b32_e32 v168, 1, v52
	v_lshl_add_u32 v60, s4, 6, v0
	v_and_b32_e32 v0, 63, v53
	v_lshl_add_u64 v[56:57], v[54:55], 0, s[14:15]
	v_lshl_add_u64 v[58:59], s[12:13], 0, v[168:169]
	v_lshlrev_b32_e32 v62, 4, v0
	v_mov_b32_e32 v63, v169
	s_mov_b32 s16, s4
	s_branch .LBB0_452

.Lxb_done_3:
	s_waitcnt vmcnt(0)
.LBB0_519:
	s_or_b64 exec, exec, s[4:5]
	s_mov_b64 s[6:7], s[0:1]
	s_waitcnt lgkmcnt(0)
	s_barrier
	v_mbcnt_lo_u32_b32 v0, -1, 0
	v_mbcnt_hi_u32_b32 v0, -1, v0
	s_mov_b32 s4, s2
	v_add_u32_e32 v0, s3, v0
	s_nop 0
	v_lshl_add_u32 v6, s4, 9, v0
	s_mov_b32 s4, 0x20000
	v_cmp_gt_i32_e32 vcc, s4, v6
	s_and_saveexec_b64 s[4:5], vcc
	s_cbranch_execz .LBB0_524
	s_load_dwordx2 s[10:11], s[6:7], 0x90
	s_mov_b64 s[12:13], 0
	s_waitcnt lgkmcnt(0)
	s_add_u32 s6, s10, 0x11700000
	s_addc_u32 s7, s11, 0
	s_add_u32 s10, s10, 0x15700000
	s_addc_u32 s11, s11, 0

.Lxb_done_4:
	s_waitcnt vmcnt(0)
.LBB0_578:
	s_or_b64 exec, exec, s[4:5]
	s_mov_b64 s[4:5], s[0:1]
	s_waitcnt lgkmcnt(0)
	s_barrier
	v_mbcnt_lo_u32_b32 v0, -1, 0
	v_mbcnt_hi_u32_b32 v0, -1, v0
	s_mov_b32 s6, s2
	v_add_u32_e32 v0, s3, v0
	s_cmpk_gt_i32 s6, 0x3ff
	v_readfirstlane_b32 s7, v0
	s_cbranch_scc1 .LBB0_583
	s_load_dwordx2 s[10:11], s[4:5], 0x90
	s_nop 0
	s_load_dwordx2 s[4:5], s[4:5], 0x40
	v_lshlrev_b32_e32 v2, 3, v0
	v_and_b32_e32 v2, 56, v2
	v_lshlrev_b32_e32 v168, 3, v2
	s_waitcnt lgkmcnt(0)
	s_add_u32 s12, s10, 0x8700000
	s_addc_u32 s13, s11, 0
	s_lshl_b32 s26, s38, 8
	s_lshl_b64 s[14:15], s[26:27], 2
	s_add_u32 s4, s4, s14
	s_addc_u32 s5, s5, s15
	v_ashrrev_i32_e32 v89, 3, v0
	v_lshl_add_u64 v[4:5], s[10:11], 0, v[168:169]
	s_mov_b64 s[14:15], 0x100000
	s_movk_i32 s17, 0x110
	v_and_b32_e32 v3, 31, v0
	v_bfe_u32 v8, v0, 5, 1
	v_lshl_add_u64 v[80:81], v[4:5], 0, s[14:15]
	v_mul_lo_u32 v4, v89, s17
	v_lshlrev_b32_e32 v5, 1, v2
	v_and_b32_e32 v1, 63, v0
	v_lshl_add_u32 v88, v3, 2, 0
	v_add3_u32 v90, 0, v4, v5
	v_mul_u32_u24_e32 v4, 0x10c, v3
	v_lshlrev_b32_e32 v5, 4, v8
	s_ashr_i32 s16, s7, 6
	v_add3_u32 v91, v88, v4, v5
	v_or_b32_e32 v4, 32, v1
	s_lshl_b32 s14, s16, 3
	v_mul_u32_u24_e32 v4, 0x110, v4
	v_add3_u32 v92, 0, v4, v5
	v_mov_b32_e32 v4, s14
	s_movk_i32 s14, 0xffe0
	v_bfi_b32 v93, s14, v4, v0
	v_mul_lo_u32 v0, v93, s17
	s_lshl_b32 s17, s16, 7
	v_lshlrev_b32_e32 v6, 2, v1
	v_add3_u32 v94, 0, v0, v5
	v_add_u32_e32 v0, 1, v93
	s_and_b32 s14, s17, 0xfffffe00
	v_cvt_f32_i32_e32 v95, v0
	v_or_b32_e32 v0, s14, v6
	s_lshl_b32 s7, s16, 5
	v_or_b32_e32 v0, 0x80, v0
	v_lshlrev_b32_e32 v4, 2, v8
	v_cmp_gt_u32_e32 vcc, 32, v1
	v_add_u32_e32 v96, 0, v0
	v_or_b32_e32 v0, s7, v1
	v_mov_b32_e32 v1, 0x180
	v_lshl_or_b32 v0, v0, 2, v1
	v_sub_u32_e32 v1, v93, v4
	v_subrev_u32_e32 v9, 32, v93
	v_sub_u32_e32 v11, 0, v1
	v_add_u32_e32 v7, 0, v6
	v_sub_u32_e32 v6, v9, v4
	v_max_i32_e32 v1, v1, v11
	v_cvt_f32_u32_e32 v98, v1
	v_sub_u32_e32 v1, 0, v6
	v_max_i32_e32 v1, v6, v1
	v_cvt_f32_u32_e32 v99, v1
	v_or_b32_e32 v1, 1, v4
	v_sub_u32_e32 v6, v93, v1
	v_sub_u32_e32 v11, 0, v6
	v_sub_u32_e32 v1, v9, v1
	v_max_i32_e32 v6, v6, v11
	v_cvt_f32_u32_e32 v100, v6
	v_sub_u32_e32 v6, 0, v1
	v_max_i32_e32 v1, v1, v6
	v_cvt_f32_u32_e32 v101, v1
	v_or_b32_e32 v1, 2, v4
	v_sub_u32_e32 v6, v93, v1
	v_sub_u32_e32 v12, 0, v6
	v_sub_u32_e32 v11, v9, v1
	v_max_i32_e32 v6, v6, v12
	v_cvt_f32_u32_e32 v102, v6
	v_sub_u32_e32 v6, 0, v11
	v_max_i32_e32 v6, v11, v6
	v_cvt_f32_u32_e32 v103, v6
	v_or_b32_e32 v6, 3, v4
	v_sub_u32_e32 v11, v93, v6
	v_sub_u32_e32 v12, 0, v11
	v_sub_u32_e32 v6, v9, v6
	v_max_i32_e32 v11, v11, v12
	v_cvt_f32_u32_e32 v104, v11
	v_sub_u32_e32 v11, 0, v6
	v_max_i32_e32 v6, v6, v11
	v_cvt_f32_u32_e32 v105, v6
	v_or_b32_e32 v6, 8, v4
	v_sub_u32_e32 v11, v93, v6
	v_sub_u32_e32 v12, 0, v11
	v_sub_u32_e32 v6, v9, v6
	v_max_i32_e32 v11, v11, v12
	v_cvt_f32_u32_e32 v106, v11
	v_sub_u32_e32 v11, 0, v6
	v_max_i32_e32 v6, v6, v11
	v_cvt_f32_u32_e32 v107, v6
	v_or_b32_e32 v6, 9, v4
	v_sub_u32_e32 v11, v93, v6
	v_sub_u32_e32 v12, 0, v11
	v_sub_u32_e32 v6, v9, v6
	v_max_i32_e32 v11, v11, v12
	v_cvt_f32_u32_e32 v108, v11
	v_sub_u32_e32 v11, 0, v6
	v_max_i32_e32 v6, v6, v11
	v_cvt_f32_u32_e32 v109, v6
	v_or_b32_e32 v6, 10, v4
	v_sub_u32_e32 v11, v93, v6
	v_sub_u32_e32 v12, 0, v11
	v_sub_u32_e32 v6, v9, v6
	v_max_i32_e32 v11, v11, v12
	v_cvt_f32_u32_e32 v110, v11
	v_sub_u32_e32 v11, 0, v6
	v_max_i32_e32 v6, v6, v11
	v_cvt_f32_u32_e32 v111, v6
	v_or_b32_e32 v6, 11, v4
	v_sub_u32_e32 v11, v93, v6
	v_sub_u32_e32 v12, 0, v11
	v_sub_u32_e32 v6, v9, v6
	v_max_i32_e32 v11, v11, v12
	v_cvt_f32_u32_e32 v112, v11
	v_sub_u32_e32 v11, 0, v6
	v_max_i32_e32 v6, v6, v11
	v_cvt_f32_u32_e32 v113, v6
	v_or_b32_e32 v6, 16, v4
	v_sub_u32_e32 v11, v93, v6
	v_sub_u32_e32 v12, 0, v11
	v_sub_u32_e32 v6, v9, v6
	v_max_i32_e32 v11, v11, v12
	v_cvt_f32_u32_e32 v114, v11
	v_sub_u32_e32 v11, 0, v6
	v_max_i32_e32 v6, v6, v11
	v_cvt_f32_u32_e32 v115, v6
	v_or_b32_e32 v6, 17, v4
	v_sub_u32_e32 v11, v93, v6
	v_sub_u32_e32 v12, 0, v11
	v_sub_u32_e32 v6, v9, v6
	v_max_i32_e32 v11, v11, v12
	v_cvt_f32_u32_e32 v116, v11
	v_sub_u32_e32 v11, 0, v6
	v_max_i32_e32 v6, v6, v11
	v_cvt_f32_u32_e32 v117, v6
	v_or_b32_e32 v6, 18, v4
	v_sub_u32_e32 v11, v93, v6
	v_sub_u32_e32 v12, 0, v11
	v_sub_u32_e32 v6, v9, v6
	v_max_i32_e32 v11, v11, v12
	v_cvt_f32_u32_e32 v118, v11
	v_sub_u32_e32 v11, 0, v6
	v_max_i32_e32 v6, v6, v11
	v_cvt_f32_u32_e32 v119, v6
	v_or_b32_e32 v6, 19, v4
	v_sub_u32_e32 v11, v93, v6
	v_sub_u32_e32 v12, 0, v11
	v_sub_u32_e32 v6, v9, v6
	v_max_i32_e32 v11, v11, v12
	v_cvt_f32_u32_e32 v120, v11
	v_sub_u32_e32 v11, 0, v6
	v_max_i32_e32 v6, v6, v11
	v_cvt_f32_u32_e32 v121, v6
	v_or_b32_e32 v6, 24, v4
	v_sub_u32_e32 v11, v93, v6
	v_sub_u32_e32 v12, 0, v11
	v_sub_u32_e32 v6, v9, v6
	v_max_i32_e32 v11, v11, v12
	v_cvt_f32_u32_e32 v122, v11
	v_sub_u32_e32 v11, 0, v6
	v_max_i32_e32 v6, v6, v11
	v_cvt_f32_u32_e32 v123, v6
	v_or_b32_e32 v6, 25, v4
	v_sub_u32_e32 v11, v93, v6
	v_sub_u32_e32 v12, 0, v11
	v_sub_u32_e32 v6, v9, v6
	v_max_i32_e32 v11, v11, v12
	v_cvt_f32_u32_e32 v124, v11
	v_sub_u32_e32 v11, 0, v6
	v_max_i32_e32 v6, v6, v11
	v_cvt_f32_u32_e32 v125, v6
	v_or_b32_e32 v6, 26, v4
	v_sub_u32_e32 v11, v93, v6
	v_sub_u32_e32 v12, 0, v11
	v_sub_u32_e32 v6, v9, v6
	v_max_i32_e32 v11, v11, v12
	s_and_b32 s15, s7, 0x60
	v_cvt_f32_u32_e32 v126, v11
	v_sub_u32_e32 v11, 0, v6
	v_add_u32_e32 v97, 0, v0
	v_or_b32_e32 v0, s15, v4
	v_max_i32_e32 v6, v6, v11
	v_or_b32_e32 v4, 27, v4
	v_cvt_f32_u32_e32 v127, v6
	v_sub_u32_e32 v6, v93, v4
	v_sub_u32_e32 v4, v9, v4
	v_sub_u32_e32 v9, 0, v6
	v_max_i32_e32 v6, v6, v9
	v_lshlrev_b32_e32 v168, 2, v0
	s_ashr_i32 s7, s6, 31
	v_or_b32_e32 v10, s15, v3
	v_cvt_f32_u32_e32 v128, v6
	v_sub_u32_e32 v6, 0, v4
	v_lshl_add_u64 v[82:83], s[4:5], 0, v[168:169]
	s_lshl_b64 s[4:5], s[6:7], 15
	s_lshl_b32 s7, s16, 13
	v_max_i32_e32 v4, v4, v6
	v_lshlrev_b32_e32 v6, 1, v10
	v_mul_u32_u24_e32 v1, 0x110, v1
	s_and_b32 s7, s7, 0x6000
	v_cvt_f32_u32_e32 v129, v4
	v_mul_u32_u24_e32 v4, 0x440, v8
	v_add3_u32 v131, 0, v1, v6
	v_lshl_or_b32 v1, v3, 8, s7
	v_add3_u32 v130, 0, v4, v6
	v_or3_b32 v4, s4, v5, v1
	v_mov_b32_e32 v5, s5
	v_lshl_add_u64 v[4:5], s[10:11], 0, v[4:5]
	s_mov_b64 s[4:5], 0x15700080
	v_add_u32_e32 v132, 0x660, v131
	v_add_u32_e32 v133, 0x880, v131
	v_add_u32_e32 v134, 0xee0, v131
	s_lshl_b32 s15, s6, 4
	v_lshl_add_u64 v[84:85], v[4:5], 0, s[4:5]
	v_lshlrev_b32_e32 v168, 1, v2
	v_add_u32_e32 v135, s17, v7
	v_lshlrev_b32_e32 v86, 1, v0
	s_branch .LBB0_581

.Lxb_done_5:
	s_waitcnt vmcnt(0)
.LBB0_637:
	s_or_b64 exec, exec, s[4:5]
	s_mov_b64 s[10:11], s[0:1]
	s_waitcnt lgkmcnt(0)
	s_barrier
	v_mbcnt_lo_u32_b32 v0, -1, 0
	v_mbcnt_hi_u32_b32 v0, -1, v0
	s_lshl_b32 s41, s38, 17
	v_add_u32_e32 v8, s3, v0
	s_mov_b32 s64, s2
	s_bitset1_b32 s41, 16
	s_mul_hi_u32 s89, s38, 0x18000
	s_cmpk_gt_i32 s64, 0xff
	v_readfirstlane_b32 s23, v8
	s_cbranch_scc1 .LBB0_669
	s_ashr_i32 s65, s64, 31
	s_lshr_b32 s4, s65, 29
	s_add_i32 s20, s64, s4
	s_and_b32 s4, s20, -8
	s_sub_i32 s19, s64, s4
	s_cmp_gt_i32 s19, -1
	s_mov_b64 s[16:17], -1
	s_cbranch_scc0 .LBB0_640
	s_lshl_b32 s18, s19, 5
	s_mov_b64 s[16:17], 0

.Lxb_done_6:
	s_waitcnt vmcnt(0)
.LBB0_723:
	s_or_b64 exec, exec, s[4:5]
	s_mov_b64 s[4:5], s[0:1]
	s_waitcnt lgkmcnt(0)
	s_barrier
	s_load_dwordx2 s[48:49], s[4:5], 0x30
	s_load_dwordx4 s[20:23], s[4:5], 0x48
	s_load_dwordx8 s[12:19], s[4:5], 0x68
	s_load_dwordx2 s[6:7], s[4:5], 0x90
	v_mbcnt_lo_u32_b32 v0, -1, 0
	v_mbcnt_hi_u32_b32 v0, -1, v0
	s_mov_b32 s28, s2
	v_add_u32_e32 v160, s3, v0
	s_waitcnt lgkmcnt(0)
	s_add_u32 s42, s6, 0x2500000
	s_addc_u32 s43, s7, 0
	v_mov_b32_e32 v14, v160
	v_readfirstlane_b32 s26, v160
	s_cmpk_gt_i32 s28, 0x57f
	v_readfirstlane_b32 s5, v14
	s_cbranch_scc1 .LBB0_739
	v_lshlrev_b32_e32 v0, 4, v14
	v_add_u32_e32 v1, 0x2000, v0
	v_ashrrev_i32_e32 v2, 31, v1
	v_lshrrev_b32_e32 v2, 22, v2
	v_add_u32_e32 v2, v1, v2
	v_ashrrev_i32_e32 v8, 10, v2
	v_mul_i32_i24_e32 v2, 0x400, v8
	v_sub_u32_e32 v1, v1, v2
	v_lshrrev_b32_e32 v2, 4, v1
	v_bitop3_b32 v1, v2, v1, 32 bitop3:0x6c
	v_ashrrev_i32_e32 v2, 31, v1
	v_lshrrev_b32_e32 v2, 26, v2
	v_add_u32_e32 v2, v1, v2
	v_lshlrev_b32_e32 v3, 3, v8
	v_ashrrev_i32_e32 v9, 6, v2
	v_and_b32_e32 v3, -16, v3
	v_add_u32_e32 v3, v9, v3
	v_and_b32_e32 v4, 3, v9
	v_lshrrev_b32_e32 v5, 2, v3
	v_lshlrev_b32_e32 v6, 1, v3
	v_and_b32_e32 v2, 0xc0, v2
	v_and_or_b32 v4, v3, s94, v4
	v_and_b32_e32 v5, 4, v5
	v_and_b32_e32 v6, 24, v6
	v_sub_u32_e32 v1, v1, v2
	v_or3_b32 v4, v4, v5, v6
	v_lshlrev_b32_e32 v5, 5, v8
	v_ashrrev_i16_sdwa v1, v227, sext(v1) dst_sel:DWORD dst_unused:UNUSED_PAD src0_sel:DWORD src1_sel:BYTE_0
	v_and_b32_e32 v5, 32, v5
	v_bfe_i32 v10, v1, 0, 16
	s_add_u32 s29, s6, 0x6700000
	v_add_lshl_u32 v1, v5, v10, 1
	s_addc_u32 s72, s7, 0
	s_mul_i32 s10, s38, 0xb00000
	v_lshl_add_u32 v144, v4, 11, v1
	v_lshl_add_u32 v146, v3, 11, v1
	v_bfe_i32 v1, v14, 27, 1
	s_mul_hi_u32 s4, s38, 0xb00000
	s_add_u32 s73, s42, s10
	v_lshrrev_b32_e32 v1, 22, v1
	s_addc_u32 s78, s43, s4
	v_add_u32_e32 v1, v0, v1
	s_ashr_i32 s91, s28, 31
	v_and_b32_e32 v1, 0xfffffc00, v1
	s_lshr_b32 s4, s91, 29
	v_sub_u32_e32 v0, v0, v1
	s_add_i32 s4, s28, s4
	s_ashr_i32 s30, s5, 6
	v_lshrrev_b32_e32 v1, 4, v0
	v_ashrrev_i32_e32 v2, 31, v14
	s_ashr_i32 s10, s4, 3
	s_and_b32 s4, s4, -8
	s_ashr_i32 s31, s5, 8
	s_lshl_b32 s90, s30, 10
	v_bitop3_b32 v0, v1, v0, 32 bitop3:0x6c
	v_lshrrev_b32_e32 v2, 26, v2
	s_sub_i32 s4, s28, s4
	v_ashrrev_i32_e32 v1, 31, v0
	v_add_u32_e32 v2, v14, v2
	s_cmp_lt_i32 s4, 0
	s_movk_i32 s11, 0xb1
	v_lshrrev_b32_e32 v1, 26, v1
	v_ashrrev_i32_e32 v12, 6, v2
	s_cselect_b32 s11, s11, 0xb0
	v_add_u32_e32 v1, v0, v1
	v_lshlrev_b32_e32 v2, 3, v12
	s_mul_i32 s4, s11, s4
	v_ashrrev_i32_e32 v11, 6, v1
	v_and_b32_e32 v2, -16, v2
	s_add_i32 s4, s4, s10
	v_add_u32_e32 v2, v11, v2
	s_mul_hi_i32 s10, s4, 0x3e0f83e1
	v_and_b32_e32 v3, 3, v11
	v_lshrrev_b32_e32 v4, 2, v2
	v_lshlrev_b32_e32 v5, 1, v2
	v_and_b32_e32 v1, 0xc0, v1
	s_lshr_b32 s11, s10, 31
	s_ashr_i32 s10, s10, 5
	v_and_or_b32 v3, v2, s94, v3
	v_and_b32_e32 v4, 4, v4
	v_and_b32_e32 v5, 24, v5
	v_sub_u32_e32 v0, v0, v1
	s_add_i32 s10, s10, s11
	v_or3_b32 v3, v3, v4, v5
	v_lshlrev_b32_e32 v4, 5, v12
	v_ashrrev_i16_sdwa v0, v227, sext(v0) dst_sel:DWORD dst_unused:UNUSED_PAD src0_sel:DWORD src1_sel:BYTE_0
	s_mul_i32 s46, s10, 6
	v_and_b32_e32 v4, 32, v4
	v_bfe_i32 v13, v0, 0, 16
	s_sub_i32 s11, 64, s46
	v_add_lshl_u32 v0, v4, v13, 1
	s_min_u32 s47, s11, 6
	s_mulk_i32 s10, 0x84
	v_lshl_add_u32 v168, v3, 11, v0
	s_sub_i32 s50, s4, s10
	v_cvt_f32_ubyte0_e32 v3, s47
	v_cvt_f32_i32_e32 v1, s50
	v_rcp_iflag_f32_e32 v4, v3
	v_lshl_add_u32 v148, v2, 11, v0
	s_ashr_i32 s4, s50, 30
	s_or_b32 s4, s4, 1
	v_mul_f32_e32 v0, v1, v4
	v_trunc_f32_e32 v0, v0
	v_fma_f32 v1, -v0, v3, v1
	v_cvt_i32_f32_e32 v0, v0
	v_cmp_ge_f32_e64 s[10:11], |v1|, v3
	s_and_b64 s[10:11], s[10:11], exec
	s_cselect_b32 s4, s4, 0
	v_readfirstlane_b32 s10, v0
	s_add_i32 s4, s10, s4
	s_mul_i32 s10, s4, s47
	s_sub_i32 s10, s50, s10
	s_sext_i32_i16 s10, s10
	s_add_i32 s64, s46, s10
	s_ashr_i32 s65, s64, 31
	s_bfe_i64 s[46:47], s[4:5], 0x100000
	s_lshl_b64 s[10:11], s[64:65], 19
	s_lshl_b64 s[46:47], s[46:47], 19
	s_add_u32 s66, s73, s46
	s_addc_u32 s67, s78, s47
	s_add_i32 s65, s90, 0
	s_add_i32 m0, s65, 0x10000
	s_mov_b64 s[80:81], s[92:93]
	global_load_lds_dwordx4 v168, s[66:67]
	s_add_i32 m0, s65, 0x12000
	s_add_u32 s46, s66, 0x40000
	global_load_lds_dwordx4 v144, s[66:67]
	s_addc_u32 s47, s67, 0
	s_add_i32 m0, s65, 0x14000
	v_mov_b32_e32 v145, v169
	global_load_lds_dwordx4 v168, s[46:47]
	s_add_i32 m0, s65, 0x16000
	s_add_u32 s68, s29, s10
	s_addc_u32 s69, s72, s11
	s_add_i32 s92, s65, 0x2000
	global_load_lds_dwordx4 v144, s[46:47]
	s_mov_b32 m0, s65
	s_add_u32 s10, s68, 0x40000
	global_load_lds_dwordx4 v148, s[68:69]
	s_mov_b32 m0, s92
	s_addc_u32 s11, s69, 0
	s_add_i32 s93, s65, 0x4000
	global_load_lds_dwordx4 v146, s[68:69]
	s_mov_b32 m0, s93
	s_add_i32 s94, s65, 0x6000
	global_load_lds_dwordx4 v148, s[10:11]
	s_mov_b32 m0, s94
	v_mov_b32_e32 v149, v169
	global_load_lds_dwordx4 v146, s[10:11]
	v_mov_b32_e32 v147, v169
	s_cmp_eq_u32 s31, 1
	s_mov_b32 s86, s89
	s_mov_b32 s97, s87
	s_mov_b32 s87, s95
	v_lshl_add_u64 v[6:7], s[66:67], 0, v[168:169]
	v_lshl_add_u64 v[4:5], s[66:67], 0, v[144:145]
	v_lshl_add_u64 v[0:1], s[68:69], 0, v[148:149]
	s_cselect_b64 s[10:11], -1, 0
	s_cmp_lg_u32 s31, 1
	v_lshl_add_u64 v[2:3], s[68:69], 0, v[146:147]
	s_cbranch_scc1 .LBB0_726
	s_barrier

.LBB0_785:
	s_or_b64 exec, exec, s[16:17]
	v_cvt_f32_u32_e32 v4, v2
	s_waitcnt vmcnt(0)
	v_readfirstlane_b32 s14, v3
	v_sub_u32_e32 v3, 0, v2
	v_rcp_iflag_f32_e32 v4, v4
	v_add_u32_e32 v5, s14, v1
	v_mul_f32_e32 v4, 0x4f7ffffe, v4
	v_cvt_u32_f32_e32 v4, v4
	v_mul_lo_u32 v1, v3, v4
	v_mul_hi_u32 v1, v4, v1
	v_add_u32_e32 v1, v4, v1
	v_mul_hi_u32 v1, v5, v1
	v_mul_lo_u32 v3, v1, v2
	v_sub_u32_e32 v3, v5, v3
	v_add_u32_e32 v4, 1, v1
	v_cmp_ge_u32_e32 vcc, v3, v2
	s_nop 1
	v_cndmask_b32_e32 v1, v1, v4, vcc
	v_sub_u32_e32 v4, v3, v2
	v_cndmask_b32_e32 v3, v3, v4, vcc
	v_add_u32_e32 v4, 1, v1
	v_cmp_ge_u32_e32 vcc, v3, v2
	v_add_u32_e32 v3, 1, v5
	s_nop 0
	v_cndmask_b32_e32 v1, v1, v4, vcc
	v_mul_lo_u32 v4, v2, v1
	v_add_u32_e32 v2, v4, v2
	v_cmp_ne_u32_e32 vcc, v3, v2
	s_waitcnt lgkmcnt(0)
	v_mad_u32_u24 v1, v1, v0, v0
	v_mov_b32_e32 v3, 0
	s_add_u32 s18, s12, 0x2400
	s_addc_u32 s19, s13, 0
	s_mov_b32 s26, 0
	s_cbranch_vccnz .Lxb_poll_7
	buffer_wbl2 sc1
	v_mov_b32_e32 v0, 0x3400
	v_mov_b32_e32 v2, 1
	s_waitcnt vmcnt(0)
	global_atomic_add v0, v2, s[6:7] offset:0
	global_atomic_add v0, v2, s[6:7] offset:256
	global_atomic_add v0, v2, s[6:7] offset:512
	global_atomic_add v0, v2, s[6:7] offset:768
	global_atomic_add v0, v2, s[6:7] offset:1024
	global_atomic_add v0, v2, s[6:7] offset:1280
	global_atomic_add v0, v2, s[6:7] offset:1536
	global_atomic_add v0, v2, s[6:7] offset:1792
	global_atomic_add v0, v2, s[6:7] offset:2048
	global_atomic_add v0, v2, s[6:7] offset:2304
	global_atomic_add v0, v2, s[6:7] offset:2560
	global_atomic_add v0, v2, s[6:7] offset:2816
	global_atomic_add v0, v2, s[6:7] offset:3072
	global_atomic_add v0, v2, s[6:7] offset:3328
	global_atomic_add v0, v2, s[6:7] offset:3584
	global_atomic_add v0, v2, s[6:7] offset:3840

.Lxb_done_7:
	s_waitcnt vmcnt(0)
.LBB0_819:
	s_or_b64 exec, exec, s[4:5]
	s_mov_b64 s[6:7], s[0:1]
	s_waitcnt lgkmcnt(0)
	s_barrier
	s_load_dwordx2 s[4:5], s[6:7], 0x20
	s_load_dwordx4 s[12:15], s[6:7], 0x88
	v_mbcnt_lo_u32_b32 v0, -1, 0
	v_mbcnt_hi_u32_b32 v0, -1, v0
	s_mov_b32 s28, s2
	v_add_u32_e32 v8, s3, v0
	s_cmpk_lt_i32 s28, 0x100
	s_cselect_b64 s[6:7], -1, 0
	s_cmpk_gt_i32 s28, 0xff
	v_readfirstlane_b32 s22, v8
	s_cbranch_scc0 .LBB0_822
	s_andn2_b64 vcc, exec, s[6:7]
	s_cbranch_vccz .LBB0_827

.Lxb_done_8:
	s_waitcnt vmcnt(0)
	s_branch .LBB0_212
